# HGRN2 output-gate (gnorm) loop software-pipelined two rows ahead (two alternating load register sets, counted waits) instead of load-wait-compute per row
# speedup vs baseline: 1.0002x; 1.0002x over previous
.LBB0_482:
	s_mov_b64 s[6:7], 0x8000000
	v_lshl_add_u64 v[120:121], v[18:19], 0, s[6:7]
	s_mov_b32 s98, 0
	v_lshl_add_u64 v[112:113], v[18:19], 0, s[6:7]
	global_load_dwordx4 v[80:83], v[18:19], off offset:16
	global_load_dwordx4 v[84:87], v[112:113], off
	global_load_dwordx4 v[88:91], v[112:113], off offset:16
	global_load_dwordx4 v[92:95], v[18:19], off
	v_lshl_add_u64 v[18:19], v[18:19], 0, s[36:37]
	s_add_i32 s99, s0, s24
	s_cmp_lt_i32 s99, 0x10000
	s_cbranch_scc0 .Lgn_loop
	v_lshl_add_u64 v[112:113], v[18:19], 0, s[6:7]
	global_load_dwordx4 v[96:99], v[18:19], off offset:16
	global_load_dwordx4 v[100:103], v[112:113], off
	global_load_dwordx4 v[104:107], v[112:113], off offset:16
	global_load_dwordx4 v[108:111], v[18:19], off
	v_lshl_add_u64 v[18:19], v[18:19], 0, s[36:37]
.Lgn_loop:
	s_add_i32 s99, s0, s24
	s_cmp_lt_i32 s99, 0x10000
	s_cselect_b32 s100, 4, 0
	s_min_u32 s101, s98, 2
	s_lshl_b32 s101, s101, 1
	s_add_i32 s100, s100, s101
	s_cmp_eq_u32 s100, 8
	s_cbranch_scc1 .Lgn_w8
	s_cmp_eq_u32 s100, 6
	s_cbranch_scc1 .Lgn_w6
	s_cmp_eq_u32 s100, 4
	s_cbranch_scc1 .Lgn_w4
	s_cmp_eq_u32 s100, 2
	s_cbranch_scc1 .Lgn_w2
	s_waitcnt vmcnt(0)
	s_branch .Lgn_wd
.Lgn_w8:
	s_waitcnt vmcnt(8)
	s_branch .Lgn_wd
.Lgn_w6:
	s_waitcnt vmcnt(6)
	s_branch .Lgn_wd
.Lgn_w4:
	s_waitcnt vmcnt(4)
	s_branch .Lgn_wd
.Lgn_w2:
	s_waitcnt vmcnt(2)
.Lgn_wd:
	s_add_i32 s99, s99, s24
	s_cmp_lt_i32 s99, 0x10000
	s_cselect_b32 s101, 1, 0
	s_bitcmp1_b32 s98, 0
	s_cbranch_scc1 .Lgn_odd
	v_mov_b64_e32 v[26:27], v[80:81]
	v_mov_b64_e32 v[28:29], v[82:83]
	v_mov_b64_e32 v[30:31], v[84:85]
	v_mov_b64_e32 v[32:33], v[86:87]
	v_mov_b64_e32 v[34:35], v[88:89]
	v_mov_b64_e32 v[36:37], v[90:91]
	v_mov_b64_e32 v[38:39], v[92:93]
	v_mov_b64_e32 v[40:41], v[94:95]
	s_cmp_eq_u32 s101, 0
	s_cbranch_scc1 .Lgn_body
	v_lshl_add_u64 v[112:113], v[18:19], 0, s[6:7]
	global_load_dwordx4 v[80:83], v[18:19], off offset:16
	global_load_dwordx4 v[84:87], v[112:113], off
	global_load_dwordx4 v[88:91], v[112:113], off offset:16
	global_load_dwordx4 v[92:95], v[18:19], off
	v_lshl_add_u64 v[18:19], v[18:19], 0, s[36:37]
	s_branch .Lgn_body
.Lgn_odd:
	v_mov_b64_e32 v[26:27], v[96:97]
	v_mov_b64_e32 v[28:29], v[98:99]
	v_mov_b64_e32 v[30:31], v[100:101]
	v_mov_b64_e32 v[32:33], v[102:103]
	v_mov_b64_e32 v[34:35], v[104:105]
	v_mov_b64_e32 v[36:37], v[106:107]
	v_mov_b64_e32 v[38:39], v[108:109]
	v_mov_b64_e32 v[40:41], v[110:111]
	s_cmp_eq_u32 s101, 0
	s_cbranch_scc1 .Lgn_body
	v_lshl_add_u64 v[112:113], v[18:19], 0, s[6:7]
	global_load_dwordx4 v[96:99], v[18:19], off offset:16
	global_load_dwordx4 v[100:103], v[112:113], off
	global_load_dwordx4 v[104:107], v[112:113], off offset:16
	global_load_dwordx4 v[108:111], v[18:19], off
	v_lshl_add_u64 v[18:19], v[18:19], 0, s[36:37]
.Lgn_body:
	v_lshlrev_b32_e32 v52, 16, v33
	v_lshlrev_b32_e32 v42, 16, v29
	v_and_b32_e32 v43, 0xffff0000, v29
	v_lshlrev_b32_e32 v44, 16, v41
	v_and_b32_e32 v45, 0xffff0000, v41
	v_lshlrev_b32_e32 v46, 16, v28
	v_and_b32_e32 v47, 0xffff0000, v28
	v_lshlrev_b32_e32 v28, 16, v40
	v_and_b32_e32 v29, 0xffff0000, v40
	v_lshlrev_b32_e32 v40, 16, v27
	v_and_b32_e32 v41, 0xffff0000, v27
	v_lshlrev_b32_e32 v48, 16, v39
	v_and_b32_e32 v49, 0xffff0000, v39
	v_lshlrev_b32_e32 v50, 16, v26
	v_and_b32_e32 v51, 0xffff0000, v26
	v_lshlrev_b32_e32 v26, 16, v38
	v_and_b32_e32 v27, 0xffff0000, v38
	v_lshlrev_b32_e32 v38, 16, v37
	v_and_b32_e32 v39, 0xffff0000, v37
	v_and_b32_e32 v53, 0xffff0000, v33
	v_lshlrev_b32_e32 v54, 16, v36
	v_and_b32_e32 v55, 0xffff0000, v36
	v_lshlrev_b32_e32 v36, 16, v32
	v_and_b32_e32 v37, 0xffff0000, v32
	v_lshlrev_b32_e32 v32, 16, v35
	v_and_b32_e32 v33, 0xffff0000, v35
	v_lshlrev_b32_e32 v58, 16, v34
	v_and_b32_e32 v59, 0xffff0000, v34
	v_lshlrev_b32_e32 v34, 16, v30
	v_and_b32_e32 v35, 0xffff0000, v30
	v_lshlrev_b32_e32 v56, 16, v31
	v_and_b32_e32 v57, 0xffff0000, v31
	v_pk_mul_f32 v[72:73], v[34:35], v[34:35]
	v_pk_mul_f32 v[68:69], v[56:57], v[56:57]
	v_add_f32_e32 v0, v72, v73
	v_add_f32_e32 v0, v68, v0
	v_pk_mul_f32 v[64:65], v[36:37], v[36:37]
	v_add_f32_e32 v0, v69, v0
	v_add_f32_e32 v0, v64, v0
	v_pk_mul_f32 v[60:61], v[52:53], v[52:53]
	v_add_f32_e32 v0, v65, v0
	v_add_f32_e32 v0, v60, v0
	v_pk_mul_f32 v[70:71], v[58:59], v[58:59]
	v_add_f32_e32 v0, v61, v0
	v_add_f32_e32 v0, v70, v0
	v_pk_mul_f32 v[66:67], v[32:33], v[32:33]
	v_add_f32_e32 v0, v71, v0
	v_add_f32_e32 v0, v66, v0
	v_pk_mul_f32 v[62:63], v[54:55], v[54:55]
	v_add_f32_e32 v0, v67, v0
	v_add_f32_e32 v0, v62, v0
	v_pk_mul_f32 v[30:31], v[38:39], v[38:39]
	v_add_f32_e32 v0, v63, v0
	v_add_f32_e32 v0, v30, v0
	v_add_f32_e32 v0, v31, v0
	ds_bpermute_b32 v25, v22, v0
	s_waitcnt lgkmcnt(0)
	v_add_f32_e32 v0, v0, v25
	ds_bpermute_b32 v25, v23, v0
	s_waitcnt lgkmcnt(0)
	v_add_f32_e32 v0, v0, v25
	ds_bpermute_b32 v25, v24, v0
	s_waitcnt lgkmcnt(0)
	v_add_f32_e32 v0, v0, v25
	v_fmamk_f32 v0, v0, 0x3c000000, v228
	v_mul_f32_e32 v25, 0x4b800000, v0
	v_cmp_gt_f32_e32 vcc, s97, v0
	s_nop 1
	v_cndmask_b32_e32 v0, v0, v25, vcc
	v_rsq_f32_e32 v0, v0
	s_nop 0
	v_mul_f32_e32 v25, 0x45800000, v0
	v_cndmask_b32_e32 v0, v0, v25, vcc
	v_pk_mul_f32 v[30:31], v[0:1], v[34:35] op_sel_hi:[0,1]
	v_pk_mul_f32 v[34:35], v[0:1], v[58:59] op_sel_hi:[0,1]
	v_pk_mul_f32 v[56:57], v[0:1], v[56:57] op_sel_hi:[0,1]
	v_pk_mul_f32 v[32:33], v[0:1], v[32:33] op_sel_hi:[0,1]
	v_pk_mul_f32 v[36:37], v[0:1], v[36:37] op_sel_hi:[0,1]
	v_pk_mul_f32 v[52:53], v[0:1], v[52:53] op_sel_hi:[0,1]
	v_pk_mul_f32 v[54:55], v[0:1], v[54:55] op_sel_hi:[0,1]
	v_pk_mul_f32 v[38:39], v[0:1], v[38:39] op_sel_hi:[0,1]
	v_pk_mul_f32 v[30:31], v[2:3], v[30:31]
	v_pk_mul_f32 v[34:35], v[10:11], v[34:35]
	v_pk_mul_f32 v[56:57], v[4:5], v[56:57]
	v_pk_mul_f32 v[32:33], v[12:13], v[32:33]
	v_pk_mul_f32 v[36:37], v[6:7], v[36:37]
	v_pk_mul_f32 v[52:53], v[8:9], v[52:53]
	v_pk_mul_f32 v[54:55], v[14:15], v[54:55]
	v_pk_mul_f32 v[38:39], v[16:17], v[38:39]
	v_pk_mul_f32 v[26:27], v[30:31], v[26:27]
	v_pk_mul_f32 v[30:31], v[34:35], v[50:51]
	v_pk_mul_f32 v[34:35], v[56:57], v[48:49]
	v_pk_mul_f32 v[32:33], v[32:33], v[40:41]
	v_pk_mul_f32 v[28:29], v[36:37], v[28:29]
	v_pk_mul_f32 v[40:41], v[52:53], v[44:45]
	v_pk_mul_f32 v[36:37], v[54:55], v[46:47]
	v_pk_mul_f32 v[38:39], v[38:39], v[42:43]
	v_cvt_pk_bf16_f32 v26, v26, v27
	v_cvt_pk_bf16_f32 v27, v34, v35
	v_cvt_pk_bf16_f32 v28, v28, v29
	v_cvt_pk_bf16_f32 v29, v40, v41
	v_cvt_pk_bf16_f32 v30, v30, v31
	v_cvt_pk_bf16_f32 v31, v32, v33
	v_cvt_pk_bf16_f32 v32, v36, v37
	v_cvt_pk_bf16_f32 v33, v38, v39
	global_store_dwordx4 v[120:121], v[26:29], off
	global_store_dwordx4 v[120:121], v[30:33], off offset:16
	v_lshl_add_u64 v[120:121], v[120:121], 0, s[36:37]
	s_add_i32 s98, s98, 1
	s_add_i32 s0, s0, s24
	s_cmp_lt_i32 s0, 0x10000
	s_cbranch_scc1 .Lgn_loop
